# conv1d fast path: lane-pair exchange (DPP) so every store is 16 B per lane (4 dwordx4 instead of 8 dwordx2 per block)
# speedup vs baseline: 1.0911x; 1.0911x over previous
.Lc1_top:
	v_readfirstlane_b32 s84, v43
	v_readfirstlane_b32 s85, v104
	v_readfirstlane_b32 s88, v36
	v_readfirstlane_b32 s94, v56
	v_readfirstlane_b32 s95, v57
	v_lshlrev_b32_e32 v252, 1, v36
	s_nop 1
	s_lshl_b32 s88, s88, 1
	v_subrev_u32_e32 v252, s88, v252
	v_and_b32_e32 v253, 8, v252
	v_cmp_eq_u32_e32 vcc, 0, v253
	v_add_u32_e32 v253, 0x9f8, v252
	s_nop 0
	v_cndmask_b32_e32 v253, v253, v252, vcc
	s_add_u32 s91, s84, 8
	s_cmp_gt_u32 s91, s85
	s_cbranch_scc1 .LBB0_360
	s_cmp_ge_u32 s84, 0x10000
	s_cbranch_scc1 .Lc1_ctx
	s_cmp_gt_u32 s91, 0x10000
	s_cbranch_scc1 .LBB0_360
	s_and_b32 s91, s84, 0x1fff
	s_cmp_lt_u32 s91, 2
	s_cbranch_scc1 .LBB0_360
	s_cmp_gt_u32 s91, 0x1ff7
	s_cbranch_scc1 .LBB0_360
	v_readfirstlane_b32 s86, v54
	v_readfirstlane_b32 s87, v55
	s_nop 1
	s_add_u32 s86, s86, s88
	s_addc_u32 s87, s87, 0
	s_sub_u32 s92, s86, 0x6800
	s_subb_u32 s93, s87, 0
	global_load_dwordx2 v[208:209], v252, s[92:93]
	s_add_u32 s92, s92, 0x3400
	s_addc_u32 s93, s93, 0
	global_load_dwordx2 v[212:213], v252, s[92:93]
	s_add_u32 s92, s92, 0x3400
	s_addc_u32 s93, s93, 0
	global_load_dwordx2 v[216:217], v252, s[92:93]
	s_add_u32 s92, s92, 0x3400
	s_addc_u32 s93, s93, 0
	global_load_dwordx2 v[220:221], v252, s[92:93]
	s_add_u32 s92, s92, 0x3400
	s_addc_u32 s93, s93, 0
	global_load_dwordx2 v[224:225], v252, s[92:93]
	s_add_u32 s92, s92, 0x3400
	s_addc_u32 s93, s93, 0
	global_load_dwordx2 v[228:229], v252, s[92:93]
	s_add_u32 s92, s92, 0x3400
	s_addc_u32 s93, s93, 0
	global_load_dwordx2 v[232:233], v252, s[92:93]
	s_add_u32 s92, s92, 0x3400
	s_addc_u32 s93, s93, 0
	global_load_dwordx2 v[236:237], v252, s[92:93]
	s_add_u32 s92, s92, 0x3400
	s_addc_u32 s93, s93, 0
	global_load_dwordx2 v[240:241], v252, s[92:93]
	s_add_u32 s92, s92, 0x3400
	s_addc_u32 s93, s93, 0
	global_load_dwordx2 v[244:245], v252, s[92:93]
	s_add_u32 s92, s92, 0x3400
	s_addc_u32 s93, s93, 0
	global_load_dwordx2 v[248:249], v252, s[92:93]
	s_waitcnt vmcnt(0)
	v_lshlrev_b32_e32 v210, 16, v209
	v_and_b32_e32 v211, 0xffff0000, v209
	v_and_b32_e32 v209, 0xffff0000, v208
	v_lshlrev_b32_e32 v208, 16, v208
	v_lshlrev_b32_e32 v214, 16, v213
	v_and_b32_e32 v215, 0xffff0000, v213
	v_and_b32_e32 v213, 0xffff0000, v212
	v_lshlrev_b32_e32 v212, 16, v212
	v_lshlrev_b32_e32 v218, 16, v217
	v_and_b32_e32 v219, 0xffff0000, v217
	v_and_b32_e32 v217, 0xffff0000, v216
	v_lshlrev_b32_e32 v216, 16, v216
	v_lshlrev_b32_e32 v222, 16, v221
	v_and_b32_e32 v223, 0xffff0000, v221
	v_and_b32_e32 v221, 0xffff0000, v220
	v_lshlrev_b32_e32 v220, 16, v220
	v_lshlrev_b32_e32 v226, 16, v225
	v_and_b32_e32 v227, 0xffff0000, v225
	v_and_b32_e32 v225, 0xffff0000, v224
	v_lshlrev_b32_e32 v224, 16, v224
	v_lshlrev_b32_e32 v230, 16, v229
	v_and_b32_e32 v231, 0xffff0000, v229
	v_and_b32_e32 v229, 0xffff0000, v228
	v_lshlrev_b32_e32 v228, 16, v228
	v_lshlrev_b32_e32 v234, 16, v233
	v_and_b32_e32 v235, 0xffff0000, v233
	v_and_b32_e32 v233, 0xffff0000, v232
	v_lshlrev_b32_e32 v232, 16, v232
	v_lshlrev_b32_e32 v238, 16, v237
	v_and_b32_e32 v239, 0xffff0000, v237
	v_and_b32_e32 v237, 0xffff0000, v236
	v_lshlrev_b32_e32 v236, 16, v236
	v_lshlrev_b32_e32 v242, 16, v241
	v_and_b32_e32 v243, 0xffff0000, v241
	v_and_b32_e32 v241, 0xffff0000, v240
	v_lshlrev_b32_e32 v240, 16, v240
	v_lshlrev_b32_e32 v246, 16, v245
	v_and_b32_e32 v247, 0xffff0000, v245
	v_and_b32_e32 v245, 0xffff0000, v244
	v_lshlrev_b32_e32 v244, 16, v244
	v_lshlrev_b32_e32 v250, 16, v249
	v_and_b32_e32 v251, 0xffff0000, v249
	v_and_b32_e32 v249, 0xffff0000, v248
	v_lshlrev_b32_e32 v248, 16, v248
	v_pk_fma_f32 v[208:209], v[0:1], v[208:209], v[16:17]
	v_pk_fma_f32 v[210:211], v[2:3], v[210:211], v[18:19]
	v_pk_fma_f32 v[208:209], v[4:5], v[212:213], v[208:209]
	v_pk_fma_f32 v[210:211], v[6:7], v[214:215], v[210:211]
	v_pk_fma_f32 v[208:209], v[8:9], v[216:217], v[208:209]
	v_pk_fma_f32 v[210:211], v[10:11], v[218:219], v[210:211]
	v_pk_fma_f32 v[208:209], v[12:13], v[220:221], v[208:209]
	v_pk_fma_f32 v[210:211], v[14:15], v[222:223], v[210:211]
	v_cvt_pk_bf16_f32 v208, v208, v209
	v_cvt_pk_bf16_f32 v209, v210, v211
	v_pk_fma_f32 v[212:213], v[0:1], v[212:213], v[16:17]
	v_pk_fma_f32 v[214:215], v[2:3], v[214:215], v[18:19]
	v_pk_fma_f32 v[212:213], v[4:5], v[216:217], v[212:213]
	v_pk_fma_f32 v[214:215], v[6:7], v[218:219], v[214:215]
	v_pk_fma_f32 v[212:213], v[8:9], v[220:221], v[212:213]
	v_pk_fma_f32 v[214:215], v[10:11], v[222:223], v[214:215]
	v_pk_fma_f32 v[212:213], v[12:13], v[224:225], v[212:213]
	v_pk_fma_f32 v[214:215], v[14:15], v[226:227], v[214:215]
	v_cvt_pk_bf16_f32 v212, v212, v213
	v_cvt_pk_bf16_f32 v213, v214, v215
	v_pk_fma_f32 v[216:217], v[0:1], v[216:217], v[16:17]
	v_pk_fma_f32 v[218:219], v[2:3], v[218:219], v[18:19]
	v_pk_fma_f32 v[216:217], v[4:5], v[220:221], v[216:217]
	v_pk_fma_f32 v[218:219], v[6:7], v[222:223], v[218:219]
	v_pk_fma_f32 v[216:217], v[8:9], v[224:225], v[216:217]
	v_pk_fma_f32 v[218:219], v[10:11], v[226:227], v[218:219]
	v_pk_fma_f32 v[216:217], v[12:13], v[228:229], v[216:217]
	v_pk_fma_f32 v[218:219], v[14:15], v[230:231], v[218:219]
	v_cvt_pk_bf16_f32 v216, v216, v217
	v_cvt_pk_bf16_f32 v217, v218, v219
	v_pk_fma_f32 v[220:221], v[0:1], v[220:221], v[16:17]
	v_pk_fma_f32 v[222:223], v[2:3], v[222:223], v[18:19]
	v_pk_fma_f32 v[220:221], v[4:5], v[224:225], v[220:221]
	v_pk_fma_f32 v[222:223], v[6:7], v[226:227], v[222:223]
	v_pk_fma_f32 v[220:221], v[8:9], v[228:229], v[220:221]
	v_pk_fma_f32 v[222:223], v[10:11], v[230:231], v[222:223]
	v_pk_fma_f32 v[220:221], v[12:13], v[232:233], v[220:221]
	v_pk_fma_f32 v[222:223], v[14:15], v[234:235], v[222:223]
	v_cvt_pk_bf16_f32 v220, v220, v221
	v_cvt_pk_bf16_f32 v221, v222, v223
	v_pk_fma_f32 v[224:225], v[0:1], v[224:225], v[16:17]
	v_pk_fma_f32 v[226:227], v[2:3], v[226:227], v[18:19]
	v_pk_fma_f32 v[224:225], v[4:5], v[228:229], v[224:225]
	v_pk_fma_f32 v[226:227], v[6:7], v[230:231], v[226:227]
	v_pk_fma_f32 v[224:225], v[8:9], v[232:233], v[224:225]
	v_pk_fma_f32 v[226:227], v[10:11], v[234:235], v[226:227]
	v_pk_fma_f32 v[224:225], v[12:13], v[236:237], v[224:225]
	v_pk_fma_f32 v[226:227], v[14:15], v[238:239], v[226:227]
	v_cvt_pk_bf16_f32 v224, v224, v225
	v_cvt_pk_bf16_f32 v225, v226, v227
	v_pk_fma_f32 v[228:229], v[0:1], v[228:229], v[16:17]
	v_pk_fma_f32 v[230:231], v[2:3], v[230:231], v[18:19]
	v_pk_fma_f32 v[228:229], v[4:5], v[232:233], v[228:229]
	v_pk_fma_f32 v[230:231], v[6:7], v[234:235], v[230:231]
	v_pk_fma_f32 v[228:229], v[8:9], v[236:237], v[228:229]
	v_pk_fma_f32 v[230:231], v[10:11], v[238:239], v[230:231]
	v_pk_fma_f32 v[228:229], v[12:13], v[240:241], v[228:229]
	v_pk_fma_f32 v[230:231], v[14:15], v[242:243], v[230:231]
	v_cvt_pk_bf16_f32 v228, v228, v229
	v_cvt_pk_bf16_f32 v229, v230, v231
	v_pk_fma_f32 v[232:233], v[0:1], v[232:233], v[16:17]
	v_pk_fma_f32 v[234:235], v[2:3], v[234:235], v[18:19]
	v_pk_fma_f32 v[232:233], v[4:5], v[236:237], v[232:233]
	v_pk_fma_f32 v[234:235], v[6:7], v[238:239], v[234:235]
	v_pk_fma_f32 v[232:233], v[8:9], v[240:241], v[232:233]
	v_pk_fma_f32 v[234:235], v[10:11], v[242:243], v[234:235]
	v_pk_fma_f32 v[232:233], v[12:13], v[244:245], v[232:233]
	v_pk_fma_f32 v[234:235], v[14:15], v[246:247], v[234:235]
	v_cvt_pk_bf16_f32 v232, v232, v233
	v_cvt_pk_bf16_f32 v233, v234, v235
	v_pk_fma_f32 v[236:237], v[0:1], v[236:237], v[16:17]
	v_pk_fma_f32 v[238:239], v[2:3], v[238:239], v[18:19]
	v_pk_fma_f32 v[236:237], v[4:5], v[240:241], v[236:237]
	v_pk_fma_f32 v[238:239], v[6:7], v[242:243], v[238:239]
	v_pk_fma_f32 v[236:237], v[8:9], v[244:245], v[236:237]
	v_pk_fma_f32 v[238:239], v[10:11], v[246:247], v[238:239]
	v_pk_fma_f32 v[236:237], v[12:13], v[248:249], v[236:237]
	v_pk_fma_f32 v[238:239], v[14:15], v[250:251], v[238:239]
	v_cvt_pk_bf16_f32 v236, v236, v237
	v_cvt_pk_bf16_f32 v237, v238, v239
	v_cndmask_b32_dpp v112, v212, v208, vcc quad_perm:[1,0,3,2] row_mask:0xf bank_mask:0xf
	v_cndmask_b32_dpp v113, v213, v209, vcc quad_perm:[1,0,3,2] row_mask:0xf bank_mask:0xf
	v_cndmask_b32_dpp v116, v220, v216, vcc quad_perm:[1,0,3,2] row_mask:0xf bank_mask:0xf
	v_cndmask_b32_dpp v117, v221, v217, vcc quad_perm:[1,0,3,2] row_mask:0xf bank_mask:0xf
	v_cndmask_b32_dpp v120, v228, v224, vcc quad_perm:[1,0,3,2] row_mask:0xf bank_mask:0xf
	v_cndmask_b32_dpp v121, v229, v225, vcc quad_perm:[1,0,3,2] row_mask:0xf bank_mask:0xf
	v_cndmask_b32_dpp v124, v236, v232, vcc quad_perm:[1,0,3,2] row_mask:0xf bank_mask:0xf
	v_cndmask_b32_dpp v125, v237, v233, vcc quad_perm:[1,0,3,2] row_mask:0xf bank_mask:0xf
	s_not_b64 vcc, vcc
	s_nop 1
	v_cndmask_b32_dpp v114, v208, v212, vcc quad_perm:[1,0,3,2] row_mask:0xf bank_mask:0xf
	v_cndmask_b32_dpp v115, v209, v213, vcc quad_perm:[1,0,3,2] row_mask:0xf bank_mask:0xf
	v_cndmask_b32_dpp v118, v216, v220, vcc quad_perm:[1,0,3,2] row_mask:0xf bank_mask:0xf
	v_cndmask_b32_dpp v119, v217, v221, vcc quad_perm:[1,0,3,2] row_mask:0xf bank_mask:0xf
	v_cndmask_b32_dpp v122, v224, v228, vcc quad_perm:[1,0,3,2] row_mask:0xf bank_mask:0xf
	v_cndmask_b32_dpp v123, v225, v229, vcc quad_perm:[1,0,3,2] row_mask:0xf bank_mask:0xf
	v_cndmask_b32_dpp v126, v232, v236, vcc quad_perm:[1,0,3,2] row_mask:0xf bank_mask:0xf
	v_cndmask_b32_dpp v127, v233, v237, vcc quad_perm:[1,0,3,2] row_mask:0xf bank_mask:0xf
	global_store_dwordx4 v253, v[112:115], s[94:95]
	s_add_u32 s94, s94, 0x1400
	s_addc_u32 s95, s95, 0
	global_store_dwordx4 v253, v[116:119], s[94:95]
	s_add_u32 s94, s94, 0x1400
	s_addc_u32 s95, s95, 0
	global_store_dwordx4 v253, v[120:123], s[94:95]
	s_add_u32 s94, s94, 0x1400
	s_addc_u32 s95, s95, 0
	global_store_dwordx4 v253, v[124:127], s[94:95]
	s_mov_b32 s66, 0x1a000
	s_mov_b32 s67, 0
	s_mov_b32 s68, 0x5000
	s_mov_b32 s69, 0
	v_add_u32_e32 v43, 8, v43
	v_lshl_add_u64 v[54:55], v[54:55], 0, s[66:67]
	v_lshl_add_u64 v[56:57], v[56:57], 0, s[68:69]
	s_add_u32 s84, s84, 8
	s_cmp_lt_u32 s84, s85
	s_cbranch_scc1 .Lc1_top
	s_branch .LBB0_344
.Lc1_ctx:
	s_and_b32 s91, s84, 0xff
	s_cmp_lt_u32 s91, 2
	s_cbranch_scc1 .LBB0_360
	s_cmp_gt_u32 s91, 0xf7
	s_cbranch_scc1 .LBB0_360
	s_sub_u32 s91, s84, 0x10002
	s_mul_i32 s91, s91, 0xa00
	s_add_u32 s92, s46, s91
	s_addc_u32 s93, s47, 0
	s_add_u32 s92, s92, s88
	s_addc_u32 s93, s93, 0
	global_load_dwordx2 v[208:209], v252, s[92:93]
	s_add_u32 s92, s92, 0xa00
	s_addc_u32 s93, s93, 0
	global_load_dwordx2 v[212:213], v252, s[92:93]
	s_add_u32 s92, s92, 0xa00
	s_addc_u32 s93, s93, 0
	global_load_dwordx2 v[216:217], v252, s[92:93]
	s_add_u32 s92, s92, 0xa00
	s_addc_u32 s93, s93, 0
	global_load_dwordx2 v[220:221], v252, s[92:93]
	s_add_u32 s92, s92, 0xa00
	s_addc_u32 s93, s93, 0
	global_load_dwordx2 v[224:225], v252, s[92:93]
	s_add_u32 s92, s92, 0xa00
	s_addc_u32 s93, s93, 0
	global_load_dwordx2 v[228:229], v252, s[92:93]
	s_add_u32 s92, s92, 0xa00
	s_addc_u32 s93, s93, 0
	global_load_dwordx2 v[232:233], v252, s[92:93]
	s_add_u32 s92, s92, 0xa00
	s_addc_u32 s93, s93, 0
	global_load_dwordx2 v[236:237], v252, s[92:93]
	s_add_u32 s92, s92, 0xa00
	s_addc_u32 s93, s93, 0
	global_load_dwordx2 v[240:241], v252, s[92:93]
	s_add_u32 s92, s92, 0xa00
	s_addc_u32 s93, s93, 0
	global_load_dwordx2 v[244:245], v252, s[92:93]
	s_add_u32 s92, s92, 0xa00
	s_addc_u32 s93, s93, 0
	global_load_dwordx2 v[248:249], v252, s[92:93]
	s_waitcnt vmcnt(0)
	v_lshlrev_b32_e32 v210, 16, v209
	v_and_b32_e32 v211, 0xffff0000, v209
	v_and_b32_e32 v209, 0xffff0000, v208
	v_lshlrev_b32_e32 v208, 16, v208
	v_lshlrev_b32_e32 v214, 16, v213
	v_and_b32_e32 v215, 0xffff0000, v213
	v_and_b32_e32 v213, 0xffff0000, v212
	v_lshlrev_b32_e32 v212, 16, v212
	v_lshlrev_b32_e32 v218, 16, v217
	v_and_b32_e32 v219, 0xffff0000, v217
	v_and_b32_e32 v217, 0xffff0000, v216
	v_lshlrev_b32_e32 v216, 16, v216
	v_lshlrev_b32_e32 v222, 16, v221
	v_and_b32_e32 v223, 0xffff0000, v221
	v_and_b32_e32 v221, 0xffff0000, v220
	v_lshlrev_b32_e32 v220, 16, v220
	v_lshlrev_b32_e32 v226, 16, v225
	v_and_b32_e32 v227, 0xffff0000, v225
	v_and_b32_e32 v225, 0xffff0000, v224
	v_lshlrev_b32_e32 v224, 16, v224
	v_lshlrev_b32_e32 v230, 16, v229
	v_and_b32_e32 v231, 0xffff0000, v229
	v_and_b32_e32 v229, 0xffff0000, v228
	v_lshlrev_b32_e32 v228, 16, v228
	v_lshlrev_b32_e32 v234, 16, v233
	v_and_b32_e32 v235, 0xffff0000, v233
	v_and_b32_e32 v233, 0xffff0000, v232
	v_lshlrev_b32_e32 v232, 16, v232
	v_lshlrev_b32_e32 v238, 16, v237
	v_and_b32_e32 v239, 0xffff0000, v237
	v_and_b32_e32 v237, 0xffff0000, v236
	v_lshlrev_b32_e32 v236, 16, v236
	v_lshlrev_b32_e32 v242, 16, v241
	v_and_b32_e32 v243, 0xffff0000, v241
	v_and_b32_e32 v241, 0xffff0000, v240
	v_lshlrev_b32_e32 v240, 16, v240
	v_lshlrev_b32_e32 v246, 16, v245
	v_and_b32_e32 v247, 0xffff0000, v245
	v_and_b32_e32 v245, 0xffff0000, v244
	v_lshlrev_b32_e32 v244, 16, v244
	v_lshlrev_b32_e32 v250, 16, v249
	v_and_b32_e32 v251, 0xffff0000, v249
	v_and_b32_e32 v249, 0xffff0000, v248
	v_lshlrev_b32_e32 v248, 16, v248
	v_pk_fma_f32 v[208:209], v[0:1], v[208:209], v[16:17]
	v_pk_fma_f32 v[210:211], v[2:3], v[210:211], v[18:19]
	v_pk_fma_f32 v[208:209], v[4:5], v[212:213], v[208:209]
	v_pk_fma_f32 v[210:211], v[6:7], v[214:215], v[210:211]
	v_pk_fma_f32 v[208:209], v[8:9], v[216:217], v[208:209]
	v_pk_fma_f32 v[210:211], v[10:11], v[218:219], v[210:211]
	v_pk_fma_f32 v[208:209], v[12:13], v[220:221], v[208:209]
	v_pk_fma_f32 v[210:211], v[14:15], v[222:223], v[210:211]
	v_cvt_pk_bf16_f32 v208, v208, v209
	v_cvt_pk_bf16_f32 v209, v210, v211
	v_pk_fma_f32 v[212:213], v[0:1], v[212:213], v[16:17]
	v_pk_fma_f32 v[214:215], v[2:3], v[214:215], v[18:19]
	v_pk_fma_f32 v[212:213], v[4:5], v[216:217], v[212:213]
	v_pk_fma_f32 v[214:215], v[6:7], v[218:219], v[214:215]
	v_pk_fma_f32 v[212:213], v[8:9], v[220:221], v[212:213]
	v_pk_fma_f32 v[214:215], v[10:11], v[222:223], v[214:215]
	v_pk_fma_f32 v[212:213], v[12:13], v[224:225], v[212:213]
	v_pk_fma_f32 v[214:215], v[14:15], v[226:227], v[214:215]
	v_cvt_pk_bf16_f32 v212, v212, v213
	v_cvt_pk_bf16_f32 v213, v214, v215
	v_pk_fma_f32 v[216:217], v[0:1], v[216:217], v[16:17]
	v_pk_fma_f32 v[218:219], v[2:3], v[218:219], v[18:19]
	v_pk_fma_f32 v[216:217], v[4:5], v[220:221], v[216:217]
	v_pk_fma_f32 v[218:219], v[6:7], v[222:223], v[218:219]
	v_pk_fma_f32 v[216:217], v[8:9], v[224:225], v[216:217]
	v_pk_fma_f32 v[218:219], v[10:11], v[226:227], v[218:219]
	v_pk_fma_f32 v[216:217], v[12:13], v[228:229], v[216:217]
	v_pk_fma_f32 v[218:219], v[14:15], v[230:231], v[218:219]
	v_cvt_pk_bf16_f32 v216, v216, v217
	v_cvt_pk_bf16_f32 v217, v218, v219
	v_pk_fma_f32 v[220:221], v[0:1], v[220:221], v[16:17]
	v_pk_fma_f32 v[222:223], v[2:3], v[222:223], v[18:19]
	v_pk_fma_f32 v[220:221], v[4:5], v[224:225], v[220:221]
	v_pk_fma_f32 v[222:223], v[6:7], v[226:227], v[222:223]
	v_pk_fma_f32 v[220:221], v[8:9], v[228:229], v[220:221]
	v_pk_fma_f32 v[222:223], v[10:11], v[230:231], v[222:223]
	v_pk_fma_f32 v[220:221], v[12:13], v[232:233], v[220:221]
	v_pk_fma_f32 v[222:223], v[14:15], v[234:235], v[222:223]
	v_cvt_pk_bf16_f32 v220, v220, v221
	v_cvt_pk_bf16_f32 v221, v222, v223
	v_pk_fma_f32 v[224:225], v[0:1], v[224:225], v[16:17]
	v_pk_fma_f32 v[226:227], v[2:3], v[226:227], v[18:19]
	v_pk_fma_f32 v[224:225], v[4:5], v[228:229], v[224:225]
	v_pk_fma_f32 v[226:227], v[6:7], v[230:231], v[226:227]
	v_pk_fma_f32 v[224:225], v[8:9], v[232:233], v[224:225]
	v_pk_fma_f32 v[226:227], v[10:11], v[234:235], v[226:227]
	v_pk_fma_f32 v[224:225], v[12:13], v[236:237], v[224:225]
	v_pk_fma_f32 v[226:227], v[14:15], v[238:239], v[226:227]
	v_cvt_pk_bf16_f32 v224, v224, v225
	v_cvt_pk_bf16_f32 v225, v226, v227
	v_pk_fma_f32 v[228:229], v[0:1], v[228:229], v[16:17]
	v_pk_fma_f32 v[230:231], v[2:3], v[230:231], v[18:19]
	v_pk_fma_f32 v[228:229], v[4:5], v[232:233], v[228:229]
	v_pk_fma_f32 v[230:231], v[6:7], v[234:235], v[230:231]
	v_pk_fma_f32 v[228:229], v[8:9], v[236:237], v[228:229]
	v_pk_fma_f32 v[230:231], v[10:11], v[238:239], v[230:231]
	v_pk_fma_f32 v[228:229], v[12:13], v[240:241], v[228:229]
	v_pk_fma_f32 v[230:231], v[14:15], v[242:243], v[230:231]
	v_cvt_pk_bf16_f32 v228, v228, v229
	v_cvt_pk_bf16_f32 v229, v230, v231
	v_pk_fma_f32 v[232:233], v[0:1], v[232:233], v[16:17]
	v_pk_fma_f32 v[234:235], v[2:3], v[234:235], v[18:19]
	v_pk_fma_f32 v[232:233], v[4:5], v[236:237], v[232:233]
	v_pk_fma_f32 v[234:235], v[6:7], v[238:239], v[234:235]
	v_pk_fma_f32 v[232:233], v[8:9], v[240:241], v[232:233]
	v_pk_fma_f32 v[234:235], v[10:11], v[242:243], v[234:235]
	v_pk_fma_f32 v[232:233], v[12:13], v[244:245], v[232:233]
	v_pk_fma_f32 v[234:235], v[14:15], v[246:247], v[234:235]
	v_cvt_pk_bf16_f32 v232, v232, v233
	v_cvt_pk_bf16_f32 v233, v234, v235
	v_pk_fma_f32 v[236:237], v[0:1], v[236:237], v[16:17]
	v_pk_fma_f32 v[238:239], v[2:3], v[238:239], v[18:19]
	v_pk_fma_f32 v[236:237], v[4:5], v[240:241], v[236:237]
	v_pk_fma_f32 v[238:239], v[6:7], v[242:243], v[238:239]
	v_pk_fma_f32 v[236:237], v[8:9], v[244:245], v[236:237]
	v_pk_fma_f32 v[238:239], v[10:11], v[246:247], v[238:239]
	v_pk_fma_f32 v[236:237], v[12:13], v[248:249], v[236:237]
	v_pk_fma_f32 v[238:239], v[14:15], v[250:251], v[238:239]
	v_cvt_pk_bf16_f32 v236, v236, v237
	v_cvt_pk_bf16_f32 v237, v238, v239
	v_cndmask_b32_dpp v112, v212, v208, vcc quad_perm:[1,0,3,2] row_mask:0xf bank_mask:0xf
	v_cndmask_b32_dpp v113, v213, v209, vcc quad_perm:[1,0,3,2] row_mask:0xf bank_mask:0xf
	v_cndmask_b32_dpp v116, v220, v216, vcc quad_perm:[1,0,3,2] row_mask:0xf bank_mask:0xf
	v_cndmask_b32_dpp v117, v221, v217, vcc quad_perm:[1,0,3,2] row_mask:0xf bank_mask:0xf
	v_cndmask_b32_dpp v120, v228, v224, vcc quad_perm:[1,0,3,2] row_mask:0xf bank_mask:0xf
	v_cndmask_b32_dpp v121, v229, v225, vcc quad_perm:[1,0,3,2] row_mask:0xf bank_mask:0xf
	v_cndmask_b32_dpp v124, v236, v232, vcc quad_perm:[1,0,3,2] row_mask:0xf bank_mask:0xf
	v_cndmask_b32_dpp v125, v237, v233, vcc quad_perm:[1,0,3,2] row_mask:0xf bank_mask:0xf
	s_not_b64 vcc, vcc
	s_nop 1
	v_cndmask_b32_dpp v114, v208, v212, vcc quad_perm:[1,0,3,2] row_mask:0xf bank_mask:0xf
	v_cndmask_b32_dpp v115, v209, v213, vcc quad_perm:[1,0,3,2] row_mask:0xf bank_mask:0xf
	v_cndmask_b32_dpp v118, v216, v220, vcc quad_perm:[1,0,3,2] row_mask:0xf bank_mask:0xf
	v_cndmask_b32_dpp v119, v217, v221, vcc quad_perm:[1,0,3,2] row_mask:0xf bank_mask:0xf
	v_cndmask_b32_dpp v122, v224, v228, vcc quad_perm:[1,0,3,2] row_mask:0xf bank_mask:0xf
	v_cndmask_b32_dpp v123, v225, v229, vcc quad_perm:[1,0,3,2] row_mask:0xf bank_mask:0xf
	v_cndmask_b32_dpp v126, v232, v236, vcc quad_perm:[1,0,3,2] row_mask:0xf bank_mask:0xf
	v_cndmask_b32_dpp v127, v233, v237, vcc quad_perm:[1,0,3,2] row_mask:0xf bank_mask:0xf
	global_store_dwordx4 v253, v[112:115], s[94:95]
	s_add_u32 s94, s94, 0x1400
	s_addc_u32 s95, s95, 0
	global_store_dwordx4 v253, v[116:119], s[94:95]
	s_add_u32 s94, s94, 0x1400
	s_addc_u32 s95, s95, 0
	global_store_dwordx4 v253, v[120:123], s[94:95]
	s_add_u32 s94, s94, 0x1400
	s_addc_u32 s95, s95, 0
	global_store_dwordx4 v253, v[124:127], s[94:95]
	s_mov_b32 s66, 0x1a000
	s_mov_b32 s67, 0
	s_mov_b32 s68, 0x5000
	s_mov_b32 s69, 0
	v_add_u32_e32 v43, 8, v43
	v_lshl_add_u64 v[54:55], v[54:55], 0, s[66:67]
	v_lshl_add_u64 v[56:57], v[56:57], 0, s[68:69]
	s_add_u32 s84, s84, 8
	s_cmp_lt_u32 s84, s85
	s_cbranch_scc1 .Lc1_top
	s_branch .LBB0_344
